# v56 + mid-C barrier moved from the end of chunk 1 to the top of chunk 2 after its 13 LDS reads are issued (counted lgkmcnt(13) covers the Y stores): barrier wait overlaps the operand read latency
# baseline (speedup 1.0000x reference)
.LBB0_580:
	ds_read_b128 v[202:205], v82 offset:128
	ds_read_b128 v[186:189], v82 offset:64
	ds_read_b128 v[182:185], v82
	ds_read_b64_tr_b16 v[170:171], v84 offset:7008
	ds_read_b64_tr_b16 v[30:31], v83
	v_add_u32_e32 v83, 0x3700, v83
	ds_read2st64_b64 v[194:197], v85 offset1:1
	ds_read_b128 v[198:201], v43
	ds_read2_b64 v[190:193], v42 offset0:8 offset1:12
	ds_read_b64_tr_b16 v[162:163], v84 offset:6944
	ds_read2_b64 v[178:181], v42 offset1:4
	ds_read_b64_tr_b16 v[166:167], v84 offset:6976
	ds_read_b64_tr_b16 v[158:159], v84 offset:6912
	ds_read_b64_tr_b16 v[38:39], v84 offset:4608
	s_cmp_lg_u32 s24, 2
	s_cbranch_scc1 .Lds_nomid
	s_waitcnt lgkmcnt(13)
	s_barrier
.Lds_nomid:
	s_waitcnt lgkmcnt(12)
	v_pk_mul_f32 v[16:17], v[16:17], v[202:203]
	v_add_u32_e32 v202, 0x800, v42
	v_add_u32_e32 v42, 0x3700, v42
	v_pk_mul_f32 v[18:19], v[18:19], v[204:205]
	s_waitcnt lgkmcnt(11)
	v_pk_mul_f32 v[14:15], v[14:15], v[188:189]
	v_cvt_pk_f16_f32 v189, v18, v19
	v_cvt_pk_f16_f32 v188, v16, v17
	s_waitcnt lgkmcnt(10)
	v_pk_mul_f32 v[6:7], v[6:7], v[184:185]
	v_pk_mul_f32 v[4:5], v[4:5], v[182:183]
	ds_read2st64_b64 v[182:185], v85 offset0:2 offset1:3
	v_add_u32_e32 v85, 0x3700, v85
	s_waitcnt lgkmcnt(9)
	v_mfma_f32_16x16x16_f16 v[170:173], v[170:171], v[30:31], v[16:19]
	v_pk_mul_f32 v[12:13], v[12:13], v[186:187]
	s_waitcnt lgkmcnt(8)
	v_mfma_f32_16x16x16_f16 v[16:19], v[194:195], v[30:31], 0
	s_waitcnt lgkmcnt(7)
	v_mul_f32_e64 v2, v2, v200
	v_mul_f32_e64 v3, v3, v201
	v_pk_mul_f32 v[0:1], v[0:1], v[198:199]
	v_cvt_pk_f16_f32 v187, v14, v15
	v_cvt_pk_f16_f32 v186, v12, v13
	v_cvt_pk_f16_f32 v201, v6, v7
	v_cvt_pk_f16_f32 v199, v2, v3
	v_cvt_pk_f16_f32 v200, v4, v5
	v_cvt_pk_f16_f32 v198, v0, v1
	s_waitcnt lgkmcnt(6)
	v_mfma_f32_16x16x32_f16 v[190:193], v[190:193], v[186:189], 0
	s_waitcnt lgkmcnt(5)
	v_mfma_f32_16x16x16_f16 v[162:165], v[162:163], v[30:31], v[4:7]
	s_waitcnt lgkmcnt(4)
	v_mfma_f32_16x16x32_f16 v[4:7], v[178:181], v[198:201], v[16:19]
	s_waitcnt lgkmcnt(3)
	v_mfma_f32_16x16x16_f16 v[12:15], v[166:167], v[30:31], v[12:15]
	ds_read_b64_tr_b16 v[174:175], v84 offset:4640
	ds_read2_b64 v[166:169], v202 offset0:40 offset1:44
	ds_read_b64_tr_b16 v[22:23], v84 offset:4672
	s_nop 3
	v_pk_add_f32 v[6:7], v[6:7], v[192:193]
	v_pk_add_f32 v[4:5], v[4:5], v[190:191]
	v_cvt_pk_f16_f32 v35, v6, v7
	v_cvt_pk_f16_f32 v34, v4, v5
	s_waitcnt lgkmcnt(3)
	s_nop 0
	v_mfma_f32_16x16x16_f16 v[4:7], v[184:185], v[34:35], 0
	v_mfma_f32_16x16x16_f16 v[158:161], v[158:159], v[30:31], v[0:3]
	s_nop 6
	s_waitcnt lgkmcnt(1)
	v_mfma_f32_16x16x32_f16 v[0:3], v[166:169], v[186:189], 0
	v_cvt_pk_f16_f32 v19, -v6, -v7
	v_cvt_pk_f16_f32 v18, -v4, -v5
	v_mfma_f32_16x16x16_f16 v[6:9], v[196:197], v[30:31], 0
	s_add_i32 s24, s24, -1
	v_mfma_f32_16x16x16_f16 v[30:33], v[38:39], v[18:19], v[158:161]
	ds_read_b64_tr_b16 v[26:27], v84 offset:4704
	v_add_u32_e32 v84, 0x3700, v84
	ds_read_b128 v[38:41], v43 offset:256
	v_add_u32_e32 v43, 0x3700, v43
	s_nop 0
	ds_read_b128 v[158:161], v82 offset:256
	v_mfma_f32_16x16x16_f16 v[34:37], v[174:175], v[18:19], v[162:165]
	s_waitcnt lgkmcnt(3)
	v_mfma_f32_16x16x16_f16 v[12:15], v[22:23], v[18:19], v[12:15]
	ds_read_b128 v[22:25], v82 offset:320
	ds_read_b128 v[162:165], v82 offset:384
	v_add_u32_e32 v82, 0x3700, v82
	v_mfma_f32_16x16x16_f16 v[166:169], v[182:183], v[18:19], v[0:3]
	s_waitcnt lgkmcnt(2)
	v_pk_mul_f32 v[4:5], v[158:159], v[34:35]
	ds_read2_b64 v[0:3], v202 offset0:32 offset1:36
	v_mfma_f32_16x16x16_f16 v[26:29], v[26:27], v[18:19], v[170:173]
	s_waitcnt lgkmcnt(2)
	v_pk_mul_f32 v[14:15], v[24:25], v[14:15]
	v_pk_mul_f32 v[12:13], v[22:23], v[12:13]
	s_waitcnt lgkmcnt(0)
	v_mfma_f32_16x16x32_f16 v[170:173], v[0:3], v[198:201], v[6:9]
	v_mul_f32_e64 v2, v40, v32
	v_mul_f32_e64 v3, v41, v33
	v_pk_mul_f32 v[0:1], v[38:39], v[30:31]
	v_pk_mul_f32 v[6:7], v[160:161], v[36:37]
	v_pk_mul_f32 v[18:19], v[164:165], v[28:29]
	v_pk_mul_f32 v[16:17], v[162:163], v[26:27]
	s_nop 1
	v_pk_add_f32 v[20:21], v[170:171], v[166:167]
	v_pk_add_f32 v[8:9], v[172:173], v[168:169]
	ds_write2st64_b32 v86, v20, v21 offset1:1
	ds_write2st64_b32 v86, v8, v9 offset0:2 offset1:3
	v_add_u32_e32 v86, 0x1000, v86
	s_cmp_lg_u32 s24, 0
	s_cbranch_scc1 .LBB0_580
	s_setprio 0
